# AP3 + the 4-MFMA sliver variants reordered so each accumulator chain is adjacent
# baseline (speedup 1.0000x reference)
; #define PG8_STAGE(bufoff, gbase, voff) do { _Pragma("unroll") for (int _i = 0; _i < 2; ++_i) \
;         __builtin_amdgcn_global_load_lds((const unsigned*)((const char*)(gbase) + (size_t)_i * qstep + (voff)[0]), (PG8_LAS unsigned*)(lds + (bufoff) + ldsw + _i * 8192), 16, 0, 0); } while (0)
; #define PG8_LDA(dst, b, h) do { _Pragma("unroll") for (int m = 0; m < 4; ++m) _Pragma("unroll") for (int k = 0; k < 2; ++k) dst[m][k] = *(const PG8_LAS bf16x8*)(lds + PG8_SA(b, h) + aoff + m * 2048 + k * 1024); } while (0)
; #define PG8_LDB(dst, b, h) do { _Pragma("unroll") for (int n = 0; n < 2; ++n) _Pragma("unroll") for (int k = 0; k < 2; ++k) dst[n][k] = *(const PG8_LAS bf16x8*)(lds + PG8_SB(b, h) + boff + n * 2048 + k * 1024); } while (0)
; #define PG8_MMA(ai, bj, At, Bt) do { __builtin_amdgcn_s_setprio(1); _Pragma("unroll") for (int m = 0; m < 4; ++m) _Pragma("unroll") for (int n = 0; n < 2; ++n) _Pragma("unroll") for (int k = 0; k < 2; ++k) \
;         acc[ai][bj][m][n] = __builtin_amdgcn_mfma_f32_16x16x32_bf16(Bt[n][k], At[m][k], acc[ai][bj][m][n], 0, 0, 0); __builtin_amdgcn_s_setprio(0); } while (0)
; #define PG8_WAIT_V89() do { if constexpr (SLIVER) PG8_WAIT_V(9); else PG8_WAIT_V(8); } while (0)
; #define PG8_WAIT_L(n) asm volatile("s_waitcnt lgkmcnt(" #n ")" ::: "memory")
; #define PG8_BAR __builtin_amdgcn_s_barrier()
; #define PG8_SCHED __builtin_amdgcn_sched_barrier(0)
; template <class Epi, class Sched, bool ALIGN_EPI = false, bool SP2 = false, bool SLIVER = false>
; __device__ __forceinline__ void gemm_phase(PG8_LAS unsigned char* lds, const Gemm g, const Sched& S, const Epi& E) {
;     ...
;             const bool last = (t == nt - 2);
;             const char* a1 = cA + (size_t)(t + 1) * kstep;
;             const char* a2 = last ? nA : cA + (size_t)(t + 2) * kstep; const char* b2 = last ? nB : cB + (size_t)(t + 2) * kstep;
;             const char* a3 = a2 + kstep; const char* b3 = b2 + kstep;
;             const char* s1 = cS + (size_t)(t + 1) * kstep; const char* s2 = last ? nS : cS + (size_t)(t + 2) * kstep;
;             if (last && has_next) S.a_ready(nxt);
;             if constexpr (SP2) {
;             PG8_LDB(B0, 0, 0); PG8_LDB(B1, 0, 1); PG8_SCHED; PG8_LDA(At, 0, 0); PG8_STAGE(PG8_SA(1, 1), a1 + hstep, voffA); PG8_STAGE_S(1, s1);
;             PG8_WAIT_V89(); PG8_WAIT_L(0); PG8_BAR; PG8_MMA(0, 0, At, B0); PG8_MMA(0, 1, At, B1); PG8_BAR; PG8_SCHED;
.LBB0_498:
	s_cmp_eq_u32 s66, s80
	s_cselect_b64 s[86:87], -1, 0
	s_add_u32 s40, s16, s80
	s_addc_u32 s41, s17, s81
	s_add_u32 s68, s40, 0x100
	s_addc_u32 s69, s41, 0
	s_and_b64 s[40:41], s[86:87], exec
	s_cselect_b32 s41, s55, s69
	s_cselect_b32 s40, s54, s68
	s_add_u32 s76, s12, s80
	s_addc_u32 s77, s13, s81
	s_add_i32 s78, 0, 0x10000
	s_and_b64 s[68:69], s[86:87], exec
	v_add_u32_e32 v138, s78, v239
	s_cselect_b32 s69, s83, s77
	s_cselect_b32 s68, s82, s76
	s_add_i32 s76, 0, 0x14000
	ds_read_b128 v[146:149], v138
	ds_read_b128 v[150:153], v138 offset:1024
	ds_read_b128 v[154:157], v138 offset:2048
	ds_read_b128 v[158:161], v138 offset:3072
	v_add_u32_e32 v138, s76, v239
	ds_read_b128 v[166:169], v138
	ds_read_b128 v[170:173], v138 offset:1024
	ds_read_b128 v[174:177], v138 offset:2048
	ds_read_b128 v[162:165], v138 offset:3072
	v_lshl_add_u64 v[208:209], v[188:189], 0, s[80:81]
	v_lshl_add_u64 v[224:225], v[208:209], 0, s[34:35]
	s_add_i32 m0, s96, 0xc000
	s_mov_b64 s[88:89], 0x120080
	ds_read_b128 v[138:141], v242
	ds_read_b128 v[142:145], v242 offset:1024
	ds_read_b128 v[180:183], v242 offset:2048
	ds_read_b128 v[184:187], v242 offset:3072
	ds_read_b128 v[192:195], v242 offset:4096
	ds_read_b128 v[196:199], v242 offset:5120
	ds_read_b128 v[200:203], v242 offset:6144
	ds_read_b128 v[220:223], v242 offset:7168
	global_load_lds_dwordx4 v[224:225], off
	v_lshl_add_u64 v[208:209], v[208:209], 0, s[88:89]
	s_add_i32 m0, s96, 0xe000
	s_nop 0
	global_load_lds_dwordx4 v[208:209], off
	v_lshl_add_u64 v[208:209], v[190:191], 0, s[80:81]
	s_add_i32 m0, s94, 0x20800
	s_nop 0
	global_load_lds_dword v[208:209], off
	s_waitcnt vmcnt(9)
	s_waitcnt lgkmcnt(0)
	s_setprio 1
	s_barrier
	v_mfma_f32_16x16x32_bf16 v[134:137], v[146:149], v[138:141], v[134:137]
	v_mfma_f32_16x16x32_bf16 v[134:137], v[150:153], v[142:145], v[134:137]
	v_mfma_f32_16x16x32_bf16 v[130:133], v[154:157], v[138:141], v[130:133]
	v_mfma_f32_16x16x32_bf16 v[130:133], v[158:161], v[142:145], v[130:133]
	v_mfma_f32_16x16x32_bf16 v[126:129], v[146:149], v[180:183], v[126:129]
	v_mfma_f32_16x16x32_bf16 v[126:129], v[150:153], v[184:187], v[126:129]
	v_mfma_f32_16x16x32_bf16 v[122:125], v[154:157], v[180:183], v[122:125]
	v_mfma_f32_16x16x32_bf16 v[122:125], v[158:161], v[184:187], v[122:125]
	v_mfma_f32_16x16x32_bf16 v[118:121], v[146:149], v[192:195], v[118:121]
	v_mfma_f32_16x16x32_bf16 v[118:121], v[150:153], v[196:199], v[118:121]
	v_mfma_f32_16x16x32_bf16 v[114:117], v[154:157], v[192:195], v[114:117]
	v_mfma_f32_16x16x32_bf16 v[114:117], v[158:161], v[196:199], v[114:117]
	v_mfma_f32_16x16x32_bf16 v[110:113], v[146:149], v[200:203], v[110:113]
	v_mfma_f32_16x16x32_bf16 v[110:113], v[150:153], v[220:223], v[110:113]
	v_mfma_f32_16x16x32_bf16 v[106:109], v[154:157], v[200:203], v[106:109]
	v_mfma_f32_16x16x32_bf16 v[106:109], v[158:161], v[220:223], v[106:109]
	s_setprio 0
	s_setprio 1
	v_mfma_f32_16x16x32_bf16 v[102:105], v[166:169], v[138:141], v[102:105]
	v_mfma_f32_16x16x32_bf16 v[102:105], v[170:173], v[142:145], v[102:105]
	v_mfma_f32_16x16x32_bf16 v[98:101], v[174:177], v[138:141], v[98:101]
	v_mfma_f32_16x16x32_bf16 v[98:101], v[162:165], v[142:145], v[98:101]
	v_mfma_f32_16x16x32_bf16 v[90:93], v[166:169], v[180:183], v[90:93]
	v_mfma_f32_16x16x32_bf16 v[90:93], v[170:173], v[184:187], v[90:93]
	v_mfma_f32_16x16x32_bf16 v[86:89], v[174:177], v[180:183], v[86:89]
	v_mfma_f32_16x16x32_bf16 v[86:89], v[162:165], v[184:187], v[86:89]
	v_mfma_f32_16x16x32_bf16 v[78:81], v[166:169], v[192:195], v[78:81]
	v_mfma_f32_16x16x32_bf16 v[78:81], v[170:173], v[196:199], v[78:81]
	v_mfma_f32_16x16x32_bf16 v[74:77], v[174:177], v[192:195], v[74:77]
	v_mfma_f32_16x16x32_bf16 v[74:77], v[162:165], v[196:199], v[74:77]
	v_mfma_f32_16x16x32_bf16 v[70:73], v[166:169], v[200:203], v[70:73]
	v_mfma_f32_16x16x32_bf16 v[70:73], v[170:173], v[220:223], v[70:73]
	v_mfma_f32_16x16x32_bf16 v[66:69], v[174:177], v[200:203], v[66:69]
	v_mfma_f32_16x16x32_bf16 v[66:69], v[162:165], v[220:223], v[66:69]
	s_barrier
; #define PG8_SB(B) __builtin_amdgcn_rcpf(1.f + expneg(B))
; #define PG8_SB(B) __builtin_amdgcn_rcpf(1.f + expneg(B))
; #define PG8_STAGE(bufoff, gbase, voff) do { _Pragma("unroll") for (int _i = 0; _i < 2; ++_i) \
;         __builtin_amdgcn_global_load_lds((const unsigned*)((const char*)(gbase) + (size_t)_i * qstep + (voff)[0]), (PG8_LAS unsigned*)(lds + (bufoff) + ldsw + _i * 8192), 16, 0, 0); } while (0)
; #define PG8_LDA(dst, b, h) do { _Pragma("unroll") for (int m = 0; m < 4; ++m) _Pragma("unroll") for (int k = 0; k < 2; ++k) dst[m][k] = *(const PG8_LAS bf16x8*)(lds + PG8_SA(b, h) + aoff + m * 2048 + k * 1024); } while (0)
; #define PG8_MMA(ai, bj, At, Bt) do { __builtin_amdgcn_s_setprio(1); _Pragma("unroll") for (int m = 0; m < 4; ++m) _Pragma("unroll") for (int n = 0; n < 2; ++n) _Pragma("unroll") for (int k = 0; k < 2; ++k) \
;         acc[ai][bj][m][n] = __builtin_amdgcn_mfma_f32_16x16x32_bf16(Bt[n][k], At[m][k], acc[ai][bj][m][n], 0, 0, 0); __builtin_amdgcn_s_setprio(0); } while (0)
; #define PG8_WAIT_V89() do { if constexpr (SLIVER) PG8_WAIT_V(9); else PG8_WAIT_V(8); } while (0)
; #define PG8_LDS_S(b) do { if constexpr (SLIVER) { Sf[0] = *(const PG8_LAS bf16x8*)(lds + STAGE_BYTES + (b) * 2048 + soff0); Sf[1] = *(const PG8_LAS bf16x8*)(lds + STAGE_BYTES + (b) * 2048 + (soff0 ^ 64)); } } while (0)
; #define PG8_WAIT_L(n) asm volatile("s_waitcnt lgkmcnt(" #n ")" ::: "memory")
; #define PG8_BAR __builtin_amdgcn_s_barrier()
; #define PG8_SCHED __builtin_amdgcn_sched_barrier(0)
; template <class Epi, class Sched, bool ALIGN_EPI = false, bool SP2 = false, bool SLIVER = false>
; __device__ __forceinline__ void gemm_phase(PG8_LAS unsigned char* lds, const Gemm g, const Sched& S, const Epi& E) {
;     ...
;             PG8_LDA(At, 0, 1); PG8_LDS_S(0); PG8_STAGE(PG8_SB(0, 0), b2, voffB); PG8_STAGE(PG8_SB(0, 1), b2 + hstep, voffB); PG8_STAGE(PG8_SA(0, 0), a2, voffA);
;             PG8_WAIT_V89(); PG8_WAIT_L(0); PG8_BAR; PG8_MMA(1, 0, At, B0); PG8_MMA(1, 1, At, B1); PG8_MMA_S(); PG8_BAR; PG8_SCHED;
	s_setprio 0
	s_add_i32 s77, 0, 0x20000
	v_lshl_add_u64 v[192:193], s[68:69], 0, v[212:213]
	s_add_i32 s68, s78, s95
	v_add_u32_e32 v178, s77, v240
	v_add_u32_e32 v184, s77, v241
	s_mov_b32 m0, s68
	s_mov_b64 s[88:89], 0x60000
	ds_read_b128 v[138:141], v242 offset:16384
	ds_read_b128 v[142:145], v242 offset:17408
	ds_read_b128 v[196:199], v242 offset:18432
	ds_read_b128 v[200:203], v242 offset:19456
	ds_read_b128 v[220:223], v242 offset:20480
	ds_read_b128 v[224:227], v242 offset:21504
	ds_read_b128 v[228:231], v242 offset:22528
	ds_read_b128 v[232:235], v242 offset:23552
	ds_read_b128 v[180:183], v178
	ds_read_b128 v[184:187], v184
	global_load_lds_dwordx4 v[192:193], off
	v_lshl_add_u64 v[194:195], v[192:193], 0, s[88:89]
	s_add_i32 m0, s68, 0x2000
	s_add_i32 s68, s76, s95
	global_load_lds_dwordx4 v[194:195], off
	v_lshl_add_u64 v[194:195], v[192:193], 0, s[24:25]
	s_mov_b32 m0, s68
	s_nop 0
	global_load_lds_dwordx4 v[194:195], off
	v_lshl_add_u64 v[194:195], v[192:193], 0, s[14:15]
	s_add_i32 m0, s68, 0x2000
	s_nop 0
	global_load_lds_dwordx4 v[194:195], off
	v_lshl_add_u64 v[194:195], s[40:41], 0, v[210:211]
	s_mov_b32 m0, s96
	v_lshl_add_u64 v[208:209], v[194:195], 0, s[88:89]
	global_load_lds_dwordx4 v[194:195], off
	s_mov_b32 m0, s19
	s_nop 0
	global_load_lds_dwordx4 v[208:209], off
	s_waitcnt vmcnt(9)
	s_waitcnt lgkmcnt(0)
	s_setprio 1
	s_barrier
	v_mfma_f32_16x16x32_bf16 v[62:65], v[146:149], v[138:141], v[62:65]
	v_mfma_f32_16x16x32_bf16 v[62:65], v[150:153], v[142:145], v[62:65]
	v_mfma_f32_16x16x32_bf16 v[58:61], v[154:157], v[138:141], v[58:61]
	v_mfma_f32_16x16x32_bf16 v[58:61], v[158:161], v[142:145], v[58:61]
	v_mfma_f32_16x16x32_bf16 v[54:57], v[146:149], v[196:199], v[54:57]
	v_mfma_f32_16x16x32_bf16 v[54:57], v[150:153], v[200:203], v[54:57]
	v_mfma_f32_16x16x32_bf16 v[50:53], v[154:157], v[196:199], v[50:53]
	v_mfma_f32_16x16x32_bf16 v[50:53], v[158:161], v[200:203], v[50:53]
	v_mfma_f32_16x16x32_bf16 v[46:49], v[146:149], v[220:223], v[46:49]
	v_mfma_f32_16x16x32_bf16 v[46:49], v[150:153], v[224:227], v[46:49]
	v_mfma_f32_16x16x32_bf16 v[42:45], v[154:157], v[220:223], v[42:45]
	v_mfma_f32_16x16x32_bf16 v[42:45], v[158:161], v[224:227], v[42:45]
	v_mfma_f32_16x16x32_bf16 v[38:41], v[146:149], v[228:231], v[38:41]
	v_mfma_f32_16x16x32_bf16 v[38:41], v[150:153], v[232:235], v[38:41]
	v_mfma_f32_16x16x32_bf16 v[34:37], v[154:157], v[228:231], v[34:37]
	v_mfma_f32_16x16x32_bf16 v[34:37], v[158:161], v[232:235], v[34:37]
	s_setprio 0
	s_setprio 1
	v_mfma_f32_16x16x32_bf16 v[30:33], v[166:169], v[138:141], v[30:33]
	v_mfma_f32_16x16x32_bf16 v[30:33], v[170:173], v[142:145], v[30:33]
	v_mfma_f32_16x16x32_bf16 v[26:29], v[174:177], v[138:141], v[26:29]
	v_mfma_f32_16x16x32_bf16 v[26:29], v[162:165], v[142:145], v[26:29]
	v_mfma_f32_16x16x32_bf16 v[22:25], v[166:169], v[196:199], v[22:25]
	v_mfma_f32_16x16x32_bf16 v[22:25], v[170:173], v[200:203], v[22:25]
	v_mfma_f32_16x16x32_bf16 v[18:21], v[174:177], v[196:199], v[18:21]
	v_mfma_f32_16x16x32_bf16 v[18:21], v[162:165], v[200:203], v[18:21]
	v_mfma_f32_16x16x32_bf16 v[14:17], v[166:169], v[220:223], v[14:17]
	v_mfma_f32_16x16x32_bf16 v[14:17], v[170:173], v[224:227], v[14:17]
	v_mfma_f32_16x16x32_bf16 v[10:13], v[174:177], v[220:223], v[10:13]
	v_mfma_f32_16x16x32_bf16 v[10:13], v[162:165], v[224:227], v[10:13]
	v_mfma_f32_16x16x32_bf16 v[6:9], v[166:169], v[228:231], v[6:9]
	v_mfma_f32_16x16x32_bf16 v[6:9], v[170:173], v[232:235], v[6:9]
	v_mfma_f32_16x16x32_bf16 v[2:5], v[174:177], v[228:231], v[2:5]
	v_mfma_f32_16x16x32_bf16 v[2:5], v[162:165], v[232:235], v[2:5]
	s_setprio 0
	s_setprio 1
	s_and_b64 vcc, exec, s[52:53]
	s_cbranch_vccz .Lslv_b0
	v_mfma_f32_16x16x32_bf16 v[138:141], v[166:169], v[180:183], v[82:85]
	v_mfma_f32_16x16x32_bf16 v[138:141], v[170:173], v[184:187], v[138:141]
	v_mfma_f32_16x16x32_bf16 v[142:145], v[174:177], v[180:183], v[94:97]
	v_mfma_f32_16x16x32_bf16 v[142:145], v[162:165], v[184:187], v[142:145]
	s_branch .LBB0_502

; #define PG8_STAGE(bufoff, gbase, voff) do { _Pragma("unroll") for (int _i = 0; _i < 2; ++_i) \
;         __builtin_amdgcn_global_load_lds((const unsigned*)((const char*)(gbase) + (size_t)_i * qstep + (voff)[0]), (PG8_LAS unsigned*)(lds + (bufoff) + ldsw + _i * 8192), 16, 0, 0); } while (0)
; #define PG8_LDA(dst, b, h) do { _Pragma("unroll") for (int m = 0; m < 4; ++m) _Pragma("unroll") for (int k = 0; k < 2; ++k) dst[m][k] = *(const PG8_LAS bf16x8*)(lds + PG8_SA(b, h) + aoff + m * 2048 + k * 1024); } while (0)
; #define PG8_LDB(dst, b, h) do { _Pragma("unroll") for (int n = 0; n < 2; ++n) _Pragma("unroll") for (int k = 0; k < 2; ++k) dst[n][k] = *(const PG8_LAS bf16x8*)(lds + PG8_SB(b, h) + boff + n * 2048 + k * 1024); } while (0)
; #define PG8_MMA(ai, bj, At, Bt) do { __builtin_amdgcn_s_setprio(1); _Pragma("unroll") for (int m = 0; m < 4; ++m) _Pragma("unroll") for (int n = 0; n < 2; ++n) _Pragma("unroll") for (int k = 0; k < 2; ++k) \
;         acc[ai][bj][m][n] = __builtin_amdgcn_mfma_f32_16x16x32_bf16(Bt[n][k], At[m][k], acc[ai][bj][m][n], 0, 0, 0); __builtin_amdgcn_s_setprio(0); } while (0)
; #define PG8_WAIT_V89() do { if constexpr (SLIVER) PG8_WAIT_V(9); else PG8_WAIT_V(8); } while (0)
; #define PG8_STAGE_S(b, gbase) do { if constexpr (SLIVER) __builtin_amdgcn_global_load_lds((const unsigned*)((const char*)(gbase) + voffS), (PG8_LAS unsigned*)(lds + STAGE_BYTES + (b) * 2048 + wid * 256), 4, 0, 0); } while (0)
; #define PG8_WAIT_L(n) asm volatile("s_waitcnt lgkmcnt(" #n ")" ::: "memory")
; #define PG8_BAR __builtin_amdgcn_s_barrier()
; #define PG8_SCHED __builtin_amdgcn_sched_barrier(0)
; template <class Epi, class Sched, bool ALIGN_EPI = false, bool SP2 = false, bool SLIVER = false>
; __device__ __forceinline__ void gemm_phase(PG8_LAS unsigned char* lds, const Gemm g, const Sched& S, const Epi& E) {
;     ...
;             PG8_LDB(B0, 1, 0); PG8_LDB(B1, 1, 1); PG8_SCHED; PG8_LDA(At, 1, 0); PG8_STAGE(PG8_SA(0, 1), a2 + hstep, voffA); PG8_STAGE_S(0, s2);
;             PG8_WAIT_V89(); PG8_WAIT_L(0); PG8_BAR; PG8_MMA(0, 0, At, B0); PG8_MMA(0, 1, At, B1); PG8_BAR; PG8_SCHED;
.LBB0_502:
	s_barrier
	s_setprio 0
	s_add_u32 s68, s62, s80
	s_addc_u32 s69, s63, s81
	s_add_u32 s76, s68, 0x100
	s_addc_u32 s77, s69, 0
	s_and_b64 s[68:69], s[86:87], exec
	s_cselect_b32 s69, s85, s77
	s_cselect_b32 s68, s84, s76
	s_add_i32 s76, 0, 0x18000
	v_add_u32_e32 v82, s76, v239
	s_add_i32 s77, 0, 0x1c000
	ds_read_b128 v[146:149], v82
	ds_read_b128 v[150:153], v82 offset:1024
	ds_read_b128 v[154:157], v82 offset:2048
	ds_read_b128 v[158:161], v82 offset:3072
	v_add_u32_e32 v82, s77, v239
	ds_read_b128 v[166:169], v82
	ds_read_b128 v[170:173], v82 offset:1024
	ds_read_b128 v[174:177], v82 offset:2048
	ds_read_b128 v[162:165], v82 offset:3072
	s_mov_b32 m0, s91
	v_lshl_add_u64 v[208:209], v[194:195], 0, s[24:25]
	ds_read_b128 v[82:85], v242 offset:32768
	ds_read_b128 v[94:97], v242 offset:33792
	ds_read_b128 v[180:183], v242 offset:34816
	ds_read_b128 v[184:187], v242 offset:35840
	ds_read_b128 v[196:199], v242 offset:36864
	ds_read_b128 v[200:203], v242 offset:37888
	ds_read_b128 v[220:223], v242 offset:38912
	ds_read_b128 v[224:227], v242 offset:39936
	global_load_lds_dwordx4 v[208:209], off
	v_lshl_add_u64 v[208:209], v[194:195], 0, s[14:15]
	s_mov_b32 m0, s92
	s_nop 0
	global_load_lds_dwordx4 v[208:209], off
	v_lshl_add_u64 v[208:209], s[68:69], 0, v[214:215]
	s_mov_b32 m0, s93
	s_nop 0
	global_load_lds_dword v[208:209], off
	s_waitcnt vmcnt(9)
	s_waitcnt lgkmcnt(0)
	s_setprio 1
	s_barrier
	v_mfma_f32_16x16x32_bf16 v[134:137], v[146:149], v[82:85], v[134:137]
	v_mfma_f32_16x16x32_bf16 v[134:137], v[150:153], v[94:97], v[134:137]
	v_mfma_f32_16x16x32_bf16 v[130:133], v[154:157], v[82:85], v[130:133]
	v_mfma_f32_16x16x32_bf16 v[130:133], v[158:161], v[94:97], v[130:133]
	v_mfma_f32_16x16x32_bf16 v[126:129], v[146:149], v[180:183], v[126:129]
	v_mfma_f32_16x16x32_bf16 v[126:129], v[150:153], v[184:187], v[126:129]
	v_mfma_f32_16x16x32_bf16 v[122:125], v[154:157], v[180:183], v[122:125]
	v_mfma_f32_16x16x32_bf16 v[122:125], v[158:161], v[184:187], v[122:125]
	v_mfma_f32_16x16x32_bf16 v[118:121], v[146:149], v[196:199], v[118:121]
	v_mfma_f32_16x16x32_bf16 v[118:121], v[150:153], v[200:203], v[118:121]
	v_mfma_f32_16x16x32_bf16 v[114:117], v[154:157], v[196:199], v[114:117]
	v_mfma_f32_16x16x32_bf16 v[114:117], v[158:161], v[200:203], v[114:117]
	v_mfma_f32_16x16x32_bf16 v[110:113], v[146:149], v[220:223], v[110:113]
	v_mfma_f32_16x16x32_bf16 v[110:113], v[150:153], v[224:227], v[110:113]
	v_mfma_f32_16x16x32_bf16 v[106:109], v[154:157], v[220:223], v[106:109]
	v_mfma_f32_16x16x32_bf16 v[106:109], v[158:161], v[224:227], v[106:109]
	s_setprio 0
	s_setprio 1
	v_mfma_f32_16x16x32_bf16 v[102:105], v[166:169], v[82:85], v[102:105]
	v_mfma_f32_16x16x32_bf16 v[102:105], v[170:173], v[94:97], v[102:105]
	v_mfma_f32_16x16x32_bf16 v[82:85], v[174:177], v[82:85], v[98:101]
	v_mfma_f32_16x16x32_bf16 v[98:101], v[162:165], v[94:97], v[82:85]
	v_mfma_f32_16x16x32_bf16 v[82:85], v[166:169], v[180:183], v[90:93]
	v_mfma_f32_16x16x32_bf16 v[90:93], v[170:173], v[184:187], v[82:85]
	v_mfma_f32_16x16x32_bf16 v[82:85], v[174:177], v[180:183], v[86:89]
	v_mfma_f32_16x16x32_bf16 v[86:89], v[162:165], v[184:187], v[82:85]
	v_mfma_f32_16x16x32_bf16 v[78:81], v[166:169], v[196:199], v[78:81]
	v_mfma_f32_16x16x32_bf16 v[78:81], v[170:173], v[200:203], v[78:81]
	v_mfma_f32_16x16x32_bf16 v[74:77], v[174:177], v[196:199], v[74:77]
	v_mfma_f32_16x16x32_bf16 v[74:77], v[162:165], v[200:203], v[74:77]
	v_mfma_f32_16x16x32_bf16 v[70:73], v[166:169], v[220:223], v[70:73]
	v_mfma_f32_16x16x32_bf16 v[70:73], v[170:173], v[224:227], v[70:73]
	v_mfma_f32_16x16x32_bf16 v[66:69], v[174:177], v[220:223], v[66:69]
	v_mfma_f32_16x16x32_bf16 v[66:69], v[162:165], v[224:227], v[66:69]
	s_barrier
; #define PG8_SB(B) __builtin_amdgcn_rcpf(1.f + expneg(B))
; #define PG8_SB(B) __builtin_amdgcn_rcpf(1.f + expneg(B))
; #define PG8_STAGE(bufoff, gbase, voff) do { _Pragma("unroll") for (int _i = 0; _i < 2; ++_i) \
;         __builtin_amdgcn_global_load_lds((const unsigned*)((const char*)(gbase) + (size_t)_i * qstep + (voff)[0]), (PG8_LAS unsigned*)(lds + (bufoff) + ldsw + _i * 8192), 16, 0, 0); } while (0)
; #define PG8_LDA(dst, b, h) do { _Pragma("unroll") for (int m = 0; m < 4; ++m) _Pragma("unroll") for (int k = 0; k < 2; ++k) dst[m][k] = *(const PG8_LAS bf16x8*)(lds + PG8_SA(b, h) + aoff + m * 2048 + k * 1024); } while (0)
; #define PG8_MMA(ai, bj, At, Bt) do { __builtin_amdgcn_s_setprio(1); _Pragma("unroll") for (int m = 0; m < 4; ++m) _Pragma("unroll") for (int n = 0; n < 2; ++n) _Pragma("unroll") for (int k = 0; k < 2; ++k) \
;         acc[ai][bj][m][n] = __builtin_amdgcn_mfma_f32_16x16x32_bf16(Bt[n][k], At[m][k], acc[ai][bj][m][n], 0, 0, 0); __builtin_amdgcn_s_setprio(0); } while (0)
; #define PG8_WAIT_V89() do { if constexpr (SLIVER) PG8_WAIT_V(9); else PG8_WAIT_V(8); } while (0)
; #define PG8_LDS_S(b) do { if constexpr (SLIVER) { Sf[0] = *(const PG8_LAS bf16x8*)(lds + STAGE_BYTES + (b) * 2048 + soff0); Sf[1] = *(const PG8_LAS bf16x8*)(lds + STAGE_BYTES + (b) * 2048 + (soff0 ^ 64)); } } while (0)
; #define PG8_WAIT_L(n) asm volatile("s_waitcnt lgkmcnt(" #n ")" ::: "memory")
; #define PG8_BAR __builtin_amdgcn_s_barrier()
; #define PG8_SCHED __builtin_amdgcn_sched_barrier(0)
; template <class Epi, class Sched, bool ALIGN_EPI = false, bool SP2 = false, bool SLIVER = false>
; __device__ __forceinline__ void gemm_phase(PG8_LAS unsigned char* lds, const Gemm g, const Sched& S, const Epi& E) {
;     ...
;             PG8_LDA(At, 1, 1); PG8_LDS_S(1); PG8_STAGE(PG8_SB(1, 0), b3, voffB); PG8_STAGE(PG8_SB(1, 1), b3 + hstep, voffB); PG8_STAGE(PG8_SA(1, 0), a3, voffA);
;             PG8_WAIT_V89(); PG8_WAIT_L(0); PG8_BAR; PG8_MMA(1, 0, At, B0); PG8_MMA(1, 1, At, B1); PG8_MMA_S(); PG8_BAR; PG8_SCHED;
	s_setprio 0
	s_add_i32 s68, 0, 0x20800
	v_add_u32_e32 v178, s68, v240
	v_add_u32_e32 v184, s68, v241
	s_add_i32 s68, s76, s95
	v_lshl_add_u64 v[208:209], v[192:193], 0, s[26:27]
	s_mov_b32 m0, s68
	ds_read_b128 v[82:85], v242 offset:49152
	ds_read_b128 v[94:97], v242 offset:50176
	ds_read_b128 v[196:199], v242 offset:51200
	ds_read_b128 v[200:203], v242 offset:52224
	ds_read_b128 v[220:223], v242 offset:53248
	ds_read_b128 v[224:227], v242 offset:54272
	ds_read_b128 v[228:231], v242 offset:55296
	ds_read_b128 v[232:235], v242 offset:56320
	ds_read_b128 v[180:183], v178
	ds_read_b128 v[184:187], v184
	global_load_lds_dwordx4 v[208:209], off
	v_lshl_add_u64 v[208:209], v[192:193], 0, s[72:73]
	s_add_i32 m0, s68, 0x2000
	s_add_i32 s68, s77, s95
	global_load_lds_dwordx4 v[208:209], off
	v_lshl_add_u64 v[208:209], v[192:193], 0, s[34:35]
	s_mov_b32 m0, s68
	s_mov_b64 s[76:77], 0x120080
	global_load_lds_dwordx4 v[208:209], off
	v_lshl_add_u64 v[192:193], v[192:193], 0, s[76:77]
	s_add_i32 m0, s68, 0x2000
	s_nop 0
	global_load_lds_dwordx4 v[192:193], off
	v_lshl_add_u64 v[192:193], v[194:195], 0, s[26:27]
	s_mov_b32 m0, s97
	s_nop 0
	global_load_lds_dwordx4 v[192:193], off
	v_lshl_add_u64 v[192:193], v[194:195], 0, s[72:73]
	s_mov_b32 m0, s18
	s_nop 0
	global_load_lds_dwordx4 v[192:193], off
	s_waitcnt vmcnt(9)
	s_waitcnt lgkmcnt(0)
	s_setprio 1
	s_barrier
	v_mfma_f32_16x16x32_bf16 v[62:65], v[146:149], v[82:85], v[62:65]
	v_mfma_f32_16x16x32_bf16 v[62:65], v[150:153], v[94:97], v[62:65]
	v_mfma_f32_16x16x32_bf16 v[58:61], v[154:157], v[82:85], v[58:61]
	v_mfma_f32_16x16x32_bf16 v[58:61], v[158:161], v[94:97], v[58:61]
	v_mfma_f32_16x16x32_bf16 v[54:57], v[146:149], v[196:199], v[54:57]
	v_mfma_f32_16x16x32_bf16 v[54:57], v[150:153], v[200:203], v[54:57]
	v_mfma_f32_16x16x32_bf16 v[50:53], v[154:157], v[196:199], v[50:53]
	v_mfma_f32_16x16x32_bf16 v[50:53], v[158:161], v[200:203], v[50:53]
	v_mfma_f32_16x16x32_bf16 v[46:49], v[146:149], v[220:223], v[46:49]
	v_mfma_f32_16x16x32_bf16 v[46:49], v[150:153], v[224:227], v[46:49]
	v_mfma_f32_16x16x32_bf16 v[42:45], v[154:157], v[220:223], v[42:45]
	v_mfma_f32_16x16x32_bf16 v[42:45], v[158:161], v[224:227], v[42:45]
	v_mfma_f32_16x16x32_bf16 v[38:41], v[146:149], v[228:231], v[38:41]
	v_mfma_f32_16x16x32_bf16 v[38:41], v[150:153], v[232:235], v[38:41]
	v_mfma_f32_16x16x32_bf16 v[34:37], v[154:157], v[228:231], v[34:37]
	v_mfma_f32_16x16x32_bf16 v[34:37], v[158:161], v[232:235], v[34:37]
	s_setprio 0
	s_setprio 1
	v_mfma_f32_16x16x32_bf16 v[30:33], v[166:169], v[82:85], v[30:33]
	v_mfma_f32_16x16x32_bf16 v[30:33], v[170:173], v[94:97], v[30:33]
	v_mfma_f32_16x16x32_bf16 v[26:29], v[174:177], v[82:85], v[26:29]
	v_mfma_f32_16x16x32_bf16 v[26:29], v[162:165], v[94:97], v[26:29]
	v_mfma_f32_16x16x32_bf16 v[22:25], v[166:169], v[196:199], v[22:25]
	v_mfma_f32_16x16x32_bf16 v[22:25], v[170:173], v[200:203], v[22:25]
	v_mfma_f32_16x16x32_bf16 v[18:21], v[174:177], v[196:199], v[18:21]
	v_mfma_f32_16x16x32_bf16 v[18:21], v[162:165], v[200:203], v[18:21]
	v_mfma_f32_16x16x32_bf16 v[14:17], v[166:169], v[220:223], v[14:17]
	v_mfma_f32_16x16x32_bf16 v[14:17], v[170:173], v[224:227], v[14:17]
	v_mfma_f32_16x16x32_bf16 v[10:13], v[174:177], v[220:223], v[10:13]
	v_mfma_f32_16x16x32_bf16 v[10:13], v[162:165], v[224:227], v[10:13]
	v_mfma_f32_16x16x32_bf16 v[6:9], v[166:169], v[228:231], v[6:9]
	v_mfma_f32_16x16x32_bf16 v[6:9], v[170:173], v[232:235], v[6:9]
	v_mfma_f32_16x16x32_bf16 v[2:5], v[174:177], v[228:231], v[2:5]
	v_mfma_f32_16x16x32_bf16 v[2:5], v[162:165], v[232:235], v[2:5]
	s_setprio 0
	s_setprio 1
	s_and_b64 vcc, exec, s[52:53]
	s_cbranch_vccz .Lslv_c0
	v_mfma_f32_16x16x32_bf16 v[82:85], v[166:169], v[180:183], v[138:141]
	v_mfma_f32_16x16x32_bf16 v[82:85], v[170:173], v[184:187], v[82:85]
	v_mfma_f32_16x16x32_bf16 v[94:97], v[174:177], v[180:183], v[142:145]
	v_mfma_f32_16x16x32_bf16 v[94:97], v[162:165], v[184:187], v[94:97]
	s_branch .LBB0_497
.LBB0_504:
.Lslv_c0:
	v_mfma_f32_16x16x32_bf16 v[82:85], v[146:149], v[180:183], v[138:141]
	v_mfma_f32_16x16x32_bf16 v[82:85], v[150:153], v[184:187], v[82:85]
	v_mfma_f32_16x16x32_bf16 v[94:97], v[154:157], v[180:183], v[142:145]
	v_mfma_f32_16x16x32_bf16 v[94:97], v[158:161], v[184:187], v[94:97]
	s_branch .LBB0_497

; #define PG8_STAGE(bufoff, gbase, voff) do { _Pragma("unroll") for (int _i = 0; _i < 2; ++_i) \
;         __builtin_amdgcn_global_load_lds((const unsigned*)((const char*)(gbase) + (size_t)_i * qstep + (voff)[0]), (PG8_LAS unsigned*)(lds + (bufoff) + ldsw + _i * 8192), 16, 0, 0); } while (0)
; #define PG8_LDA(dst, b, h) do { _Pragma("unroll") for (int m = 0; m < 4; ++m) _Pragma("unroll") for (int k = 0; k < 2; ++k) dst[m][k] = *(const PG8_LAS bf16x8*)(lds + PG8_SA(b, h) + aoff + m * 2048 + k * 1024); } while (0)
; #define PG8_LDB(dst, b, h) do { _Pragma("unroll") for (int n = 0; n < 2; ++n) _Pragma("unroll") for (int k = 0; k < 2; ++k) dst[n][k] = *(const PG8_LAS bf16x8*)(lds + PG8_SB(b, h) + boff + n * 2048 + k * 1024); } while (0)
; #define PG8_MMA(ai, bj, At, Bt) do { __builtin_amdgcn_s_setprio(1); _Pragma("unroll") for (int m = 0; m < 4; ++m) _Pragma("unroll") for (int n = 0; n < 2; ++n) _Pragma("unroll") for (int k = 0; k < 2; ++k) \
;         acc[ai][bj][m][n] = __builtin_amdgcn_mfma_f32_16x16x32_bf16(Bt[n][k], At[m][k], acc[ai][bj][m][n], 0, 0, 0); __builtin_amdgcn_s_setprio(0); } while (0)
; #define PG8_WAIT_V89() do { if constexpr (SLIVER) PG8_WAIT_V(9); else PG8_WAIT_V(8); } while (0)
; #define PG8_WAIT_L(n) asm volatile("s_waitcnt lgkmcnt(" #n ")" ::: "memory")
; #define PG8_BAR __builtin_amdgcn_s_barrier()
; #define PG8_SCHED __builtin_amdgcn_sched_barrier(0)
; template <class Epi, class Sched, bool ALIGN_EPI = false, bool SP2 = false, bool SLIVER = false>
; __device__ __forceinline__ void gemm_phase(PG8_LAS unsigned char* lds, const Gemm g, const Sched& S, const Epi& E) {
;     ...
;             const bool last = (t == nt - 2);
;             const char* a1 = cA + (size_t)(t + 1) * kstep;
;             const char* a2 = last ? nA : cA + (size_t)(t + 2) * kstep; const char* b2 = last ? nB : cB + (size_t)(t + 2) * kstep;
;             const char* a3 = a2 + kstep; const char* b3 = b2 + kstep;
;             const char* s1 = cS + (size_t)(t + 1) * kstep; const char* s2 = last ? nS : cS + (size_t)(t + 2) * kstep;
;             if (last && has_next) S.a_ready(nxt);
;             if constexpr (SP2) {
;             PG8_LDB(B0, 0, 0); PG8_LDB(B1, 0, 1); PG8_SCHED; PG8_LDA(At, 0, 0); PG8_STAGE(PG8_SA(1, 1), a1 + hstep, voffA); PG8_STAGE_S(1, s1);
;             PG8_WAIT_V89(); PG8_WAIT_L(0); PG8_BAR; PG8_MMA(0, 0, At, B0); PG8_MMA(0, 1, At, B1); PG8_BAR; PG8_SCHED;
.LBB0_598:
	s_add_u32 s40, s92, s62
	s_addc_u32 s41, s93, s63
	s_add_u32 s77, s40, 0x100
	s_addc_u32 s78, s41, 0
	s_add_u32 s83, s68, s62
	s_addc_u32 s79, s69, s63
	s_add_i32 s96, 0, 0x10000
	s_cmpk_eq_i32 s62, 0xf00
	s_cselect_b64 s[80:81], -1, 0
	s_and_b64 s[40:41], s[80:81], exec
	s_cselect_b32 s41, s12, s78
	s_cselect_b32 s40, s13, s77
	v_add_u32_e32 v138, s96, v212
	s_cselect_b32 s79, s17, s79
	s_cselect_b32 s78, s55, s83
	s_add_i32 s77, 0, 0x14000
	ds_read_b128 v[146:149], v138
	ds_read_b128 v[150:153], v138 offset:1024
	ds_read_b128 v[154:157], v138 offset:2048
	ds_read_b128 v[158:161], v138 offset:3072
	v_add_u32_e32 v138, s77, v212
	ds_read_b128 v[166:169], v138
	ds_read_b128 v[170:173], v138 offset:1024
	ds_read_b128 v[174:177], v138 offset:2048
	ds_read_b128 v[162:165], v138 offset:3072
	v_lshl_add_u64 v[202:203], v[200:201], 0, s[62:63]
	v_lshl_add_u64 v[208:209], v[202:203], 0, s[30:31]
	s_add_i32 m0, s85, 0xc000
	ds_read_b128 v[138:141], v215
	ds_read_b128 v[142:145], v215 offset:1024
	ds_read_b128 v[180:183], v215 offset:2048
	ds_read_b128 v[184:187], v215 offset:3072
	ds_read_b128 v[216:219], v215 offset:4096
	ds_read_b128 v[220:223], v215 offset:5120
	ds_read_b128 v[224:227], v215 offset:6144
	ds_read_b128 v[228:231], v215 offset:7168
	global_load_lds_dwordx4 v[208:209], off
	v_lshl_add_u64 v[202:203], v[202:203], 0, s[34:35]
	s_add_i32 m0, s85, 0xe000
	s_nop 0
	global_load_lds_dwordx4 v[202:203], off
	v_lshl_add_u64 v[202:203], v[198:199], 0, s[62:63]
	s_add_i32 m0, s45, 0x20800
	s_nop 0
	global_load_lds_dword v[202:203], off
	s_waitcnt vmcnt(9)
	s_waitcnt lgkmcnt(0)
	s_setprio 1
	s_barrier
	v_mfma_f32_16x16x32_bf16 v[134:137], v[146:149], v[138:141], v[134:137]
	v_mfma_f32_16x16x32_bf16 v[134:137], v[150:153], v[142:145], v[134:137]
	v_mfma_f32_16x16x32_bf16 v[130:133], v[154:157], v[138:141], v[130:133]
	v_mfma_f32_16x16x32_bf16 v[130:133], v[158:161], v[142:145], v[130:133]
	v_mfma_f32_16x16x32_bf16 v[118:121], v[146:149], v[180:183], v[118:121]
	v_mfma_f32_16x16x32_bf16 v[118:121], v[150:153], v[184:187], v[118:121]
	v_mfma_f32_16x16x32_bf16 v[114:117], v[154:157], v[180:183], v[114:117]
	v_mfma_f32_16x16x32_bf16 v[114:117], v[158:161], v[184:187], v[114:117]
	v_mfma_f32_16x16x32_bf16 v[102:105], v[146:149], v[216:219], v[102:105]
	v_mfma_f32_16x16x32_bf16 v[102:105], v[150:153], v[220:223], v[102:105]
	v_mfma_f32_16x16x32_bf16 v[98:101], v[154:157], v[216:219], v[98:101]
	v_mfma_f32_16x16x32_bf16 v[98:101], v[158:161], v[220:223], v[98:101]
	v_mfma_f32_16x16x32_bf16 v[86:89], v[146:149], v[224:227], v[86:89]
	v_mfma_f32_16x16x32_bf16 v[86:89], v[150:153], v[228:231], v[86:89]
	v_mfma_f32_16x16x32_bf16 v[82:85], v[154:157], v[224:227], v[82:85]
	v_mfma_f32_16x16x32_bf16 v[82:85], v[158:161], v[228:231], v[82:85]
	s_setprio 0
	s_setprio 1
	v_mfma_f32_16x16x32_bf16 v[126:129], v[166:169], v[138:141], v[126:129]
	v_mfma_f32_16x16x32_bf16 v[126:129], v[170:173], v[142:145], v[126:129]
	v_mfma_f32_16x16x32_bf16 v[122:125], v[174:177], v[138:141], v[122:125]
	v_mfma_f32_16x16x32_bf16 v[122:125], v[162:165], v[142:145], v[122:125]
	v_mfma_f32_16x16x32_bf16 v[110:113], v[166:169], v[180:183], v[110:113]
	v_mfma_f32_16x16x32_bf16 v[110:113], v[170:173], v[184:187], v[110:113]
	v_mfma_f32_16x16x32_bf16 v[106:109], v[174:177], v[180:183], v[106:109]
	v_mfma_f32_16x16x32_bf16 v[106:109], v[162:165], v[184:187], v[106:109]
	v_mfma_f32_16x16x32_bf16 v[94:97], v[166:169], v[216:219], v[94:97]
	v_mfma_f32_16x16x32_bf16 v[94:97], v[170:173], v[220:223], v[94:97]
	v_mfma_f32_16x16x32_bf16 v[90:93], v[174:177], v[216:219], v[90:93]
	v_mfma_f32_16x16x32_bf16 v[90:93], v[162:165], v[220:223], v[90:93]
	v_mfma_f32_16x16x32_bf16 v[78:81], v[166:169], v[224:227], v[78:81]
	v_mfma_f32_16x16x32_bf16 v[78:81], v[170:173], v[228:231], v[78:81]
	v_mfma_f32_16x16x32_bf16 v[74:77], v[174:177], v[224:227], v[74:77]
	v_mfma_f32_16x16x32_bf16 v[74:77], v[162:165], v[228:231], v[74:77]
	s_barrier
; #define PG8_SB(B) __builtin_amdgcn_rcpf(1.f + expneg(B))
; #define PG8_SB(B) __builtin_amdgcn_rcpf(1.f + expneg(B))
; #define PG8_STAGE(bufoff, gbase, voff) do { _Pragma("unroll") for (int _i = 0; _i < 2; ++_i) \
;         __builtin_amdgcn_global_load_lds((const unsigned*)((const char*)(gbase) + (size_t)_i * qstep + (voff)[0]), (PG8_LAS unsigned*)(lds + (bufoff) + ldsw + _i * 8192), 16, 0, 0); } while (0)
; #define PG8_LDA(dst, b, h) do { _Pragma("unroll") for (int m = 0; m < 4; ++m) _Pragma("unroll") for (int k = 0; k < 2; ++k) dst[m][k] = *(const PG8_LAS bf16x8*)(lds + PG8_SA(b, h) + aoff + m * 2048 + k * 1024); } while (0)
; #define PG8_MMA(ai, bj, At, Bt) do { __builtin_amdgcn_s_setprio(1); _Pragma("unroll") for (int m = 0; m < 4; ++m) _Pragma("unroll") for (int n = 0; n < 2; ++n) _Pragma("unroll") for (int k = 0; k < 2; ++k) \
;         acc[ai][bj][m][n] = __builtin_amdgcn_mfma_f32_16x16x32_bf16(Bt[n][k], At[m][k], acc[ai][bj][m][n], 0, 0, 0); __builtin_amdgcn_s_setprio(0); } while (0)
; #define PG8_WAIT_V89() do { if constexpr (SLIVER) PG8_WAIT_V(9); else PG8_WAIT_V(8); } while (0)
; #define PG8_LDS_S(b) do { if constexpr (SLIVER) { Sf[0] = *(const PG8_LAS bf16x8*)(lds + STAGE_BYTES + (b) * 2048 + soff0); Sf[1] = *(const PG8_LAS bf16x8*)(lds + STAGE_BYTES + (b) * 2048 + (soff0 ^ 64)); } } while (0)
; #define PG8_WAIT_L(n) asm volatile("s_waitcnt lgkmcnt(" #n ")" ::: "memory")
; #define PG8_BAR __builtin_amdgcn_s_barrier()
; #define PG8_SCHED __builtin_amdgcn_sched_barrier(0)
; template <class Epi, class Sched, bool ALIGN_EPI = false, bool SP2 = false, bool SLIVER = false>
; __device__ __forceinline__ void gemm_phase(PG8_LAS unsigned char* lds, const Gemm g, const Sched& S, const Epi& E) {
;     ...
;             PG8_LDA(At, 0, 1); PG8_LDS_S(0); PG8_STAGE(PG8_SB(0, 0), b2, voffB); PG8_STAGE(PG8_SB(0, 1), b2 + hstep, voffB); PG8_STAGE(PG8_SA(0, 0), a2, voffA);
;             PG8_WAIT_V89(); PG8_WAIT_L(0); PG8_BAR; PG8_MMA(1, 0, At, B0); PG8_MMA(1, 1, At, B1); PG8_MMA_S(); PG8_BAR; PG8_SCHED;
	s_setprio 0
	s_add_i32 s83, 0, 0x20000
	v_lshl_add_u64 v[202:203], s[78:79], 0, v[190:191]
	s_add_i32 s78, s96, s18
	v_add_u32_e32 v178, s83, v213
	v_add_u32_e32 v184, s83, v214
	s_mov_b32 m0, s78
	ds_read_b128 v[138:141], v215 offset:16384
	ds_read_b128 v[142:145], v215 offset:17408
	ds_read_b128 v[216:219], v215 offset:18432
	ds_read_b128 v[220:223], v215 offset:19456
	ds_read_b128 v[224:227], v215 offset:20480
	ds_read_b128 v[228:231], v215 offset:21504
	ds_read_b128 v[232:235], v215 offset:22528
	ds_read_b128 v[240:243], v215 offset:23552
	ds_read_b128 v[180:183], v178
	ds_read_b128 v[184:187], v184
	global_load_lds_dwordx4 v[202:203], off
	v_lshl_add_u64 v[208:209], v[202:203], 0, s[20:21]
	s_add_i32 m0, s78, 0x2000
	s_add_i32 s77, s77, s18
	global_load_lds_dwordx4 v[208:209], off
	v_lshl_add_u64 v[208:209], v[202:203], 0, s[22:23]
	s_mov_b32 m0, s77
	v_lshl_add_u64 v[210:211], s[40:41], 0, v[188:189]
	global_load_lds_dwordx4 v[208:209], off
	v_lshl_add_u64 v[208:209], v[202:203], 0, s[24:25]
	s_add_i32 m0, s77, 0x2000
	s_nop 0
	global_load_lds_dwordx4 v[208:209], off
	s_mov_b32 m0, s85
	v_lshl_add_u64 v[208:209], v[210:211], 0, s[20:21]
	global_load_lds_dwordx4 v[210:211], off
	s_mov_b32 m0, s19
	s_nop 0
	global_load_lds_dwordx4 v[208:209], off
	s_waitcnt vmcnt(9)
	s_waitcnt lgkmcnt(0)
	s_setprio 1
	s_barrier
	v_mfma_f32_16x16x32_bf16 v[70:73], v[146:149], v[138:141], v[70:73]
	v_mfma_f32_16x16x32_bf16 v[70:73], v[150:153], v[142:145], v[70:73]
	v_mfma_f32_16x16x32_bf16 v[66:69], v[154:157], v[138:141], v[66:69]
	v_mfma_f32_16x16x32_bf16 v[66:69], v[158:161], v[142:145], v[66:69]
	v_mfma_f32_16x16x32_bf16 v[54:57], v[146:149], v[216:219], v[54:57]
	v_mfma_f32_16x16x32_bf16 v[54:57], v[150:153], v[220:223], v[54:57]
	v_mfma_f32_16x16x32_bf16 v[50:53], v[154:157], v[216:219], v[50:53]
	v_mfma_f32_16x16x32_bf16 v[50:53], v[158:161], v[220:223], v[50:53]
	v_mfma_f32_16x16x32_bf16 v[38:41], v[146:149], v[224:227], v[38:41]
	v_mfma_f32_16x16x32_bf16 v[38:41], v[150:153], v[228:231], v[38:41]
	v_mfma_f32_16x16x32_bf16 v[34:37], v[154:157], v[224:227], v[34:37]
	v_mfma_f32_16x16x32_bf16 v[34:37], v[158:161], v[228:231], v[34:37]
	v_mfma_f32_16x16x32_bf16 v[22:25], v[146:149], v[232:235], v[22:25]
	v_mfma_f32_16x16x32_bf16 v[22:25], v[150:153], v[240:243], v[22:25]
	v_mfma_f32_16x16x32_bf16 v[18:21], v[154:157], v[232:235], v[18:21]
	v_mfma_f32_16x16x32_bf16 v[18:21], v[158:161], v[240:243], v[18:21]
	s_setprio 0
	s_setprio 1
	v_mfma_f32_16x16x32_bf16 v[62:65], v[166:169], v[138:141], v[62:65]
	v_mfma_f32_16x16x32_bf16 v[62:65], v[170:173], v[142:145], v[62:65]
	v_mfma_f32_16x16x32_bf16 v[58:61], v[174:177], v[138:141], v[58:61]
	v_mfma_f32_16x16x32_bf16 v[58:61], v[162:165], v[142:145], v[58:61]
	v_mfma_f32_16x16x32_bf16 v[46:49], v[166:169], v[216:219], v[46:49]
	v_mfma_f32_16x16x32_bf16 v[46:49], v[170:173], v[220:223], v[46:49]
	v_mfma_f32_16x16x32_bf16 v[42:45], v[174:177], v[216:219], v[42:45]
	v_mfma_f32_16x16x32_bf16 v[42:45], v[162:165], v[220:223], v[42:45]
	v_mfma_f32_16x16x32_bf16 v[30:33], v[166:169], v[224:227], v[30:33]
	v_mfma_f32_16x16x32_bf16 v[30:33], v[170:173], v[228:231], v[30:33]
	v_mfma_f32_16x16x32_bf16 v[26:29], v[174:177], v[224:227], v[26:29]
	v_mfma_f32_16x16x32_bf16 v[26:29], v[162:165], v[228:231], v[26:29]
	v_mfma_f32_16x16x32_bf16 v[14:17], v[166:169], v[232:235], v[14:17]
	v_mfma_f32_16x16x32_bf16 v[14:17], v[170:173], v[240:243], v[14:17]
	v_mfma_f32_16x16x32_bf16 v[10:13], v[174:177], v[232:235], v[10:13]
	v_mfma_f32_16x16x32_bf16 v[10:13], v[162:165], v[240:243], v[10:13]
	s_setprio 0
	s_setprio 1
	s_and_b64 vcc, exec, s[52:53]
	s_cbranch_vccz .Lslv_b1
	v_mfma_f32_16x16x32_bf16 v[138:141], v[166:169], v[180:183], v[6:9]
	v_mfma_f32_16x16x32_bf16 v[138:141], v[170:173], v[184:187], v[138:141]
	v_mfma_f32_16x16x32_bf16 v[142:145], v[174:177], v[180:183], v[2:5]
	v_mfma_f32_16x16x32_bf16 v[142:145], v[162:165], v[184:187], v[142:145]
	s_branch .LBB0_602
.LBB0_600:
.Lslv_b1:
	v_mfma_f32_16x16x32_bf16 v[6:9], v[146:149], v[180:183], v[6:9]
	v_mfma_f32_16x16x32_bf16 v[138:141], v[150:153], v[184:187], v[6:9]
	v_mfma_f32_16x16x32_bf16 v[2:5], v[154:157], v[180:183], v[2:5]
	v_mfma_f32_16x16x32_bf16 v[142:145], v[158:161], v[184:187], v[2:5]

; #define PG8_STAGE(bufoff, gbase, voff) do { _Pragma("unroll") for (int _i = 0; _i < 2; ++_i) \
;         __builtin_amdgcn_global_load_lds((const unsigned*)((const char*)(gbase) + (size_t)_i * qstep + (voff)[0]), (PG8_LAS unsigned*)(lds + (bufoff) + ldsw + _i * 8192), 16, 0, 0); } while (0)
; #define PG8_LDA(dst, b, h) do { _Pragma("unroll") for (int m = 0; m < 4; ++m) _Pragma("unroll") for (int k = 0; k < 2; ++k) dst[m][k] = *(const PG8_LAS bf16x8*)(lds + PG8_SA(b, h) + aoff + m * 2048 + k * 1024); } while (0)
; #define PG8_LDB(dst, b, h) do { _Pragma("unroll") for (int n = 0; n < 2; ++n) _Pragma("unroll") for (int k = 0; k < 2; ++k) dst[n][k] = *(const PG8_LAS bf16x8*)(lds + PG8_SB(b, h) + boff + n * 2048 + k * 1024); } while (0)
; #define PG8_MMA(ai, bj, At, Bt) do { __builtin_amdgcn_s_setprio(1); _Pragma("unroll") for (int m = 0; m < 4; ++m) _Pragma("unroll") for (int n = 0; n < 2; ++n) _Pragma("unroll") for (int k = 0; k < 2; ++k) \
;         acc[ai][bj][m][n] = __builtin_amdgcn_mfma_f32_16x16x32_bf16(Bt[n][k], At[m][k], acc[ai][bj][m][n], 0, 0, 0); __builtin_amdgcn_s_setprio(0); } while (0)
; #define PG8_WAIT_V89() do { if constexpr (SLIVER) PG8_WAIT_V(9); else PG8_WAIT_V(8); } while (0)
; #define PG8_WAIT_L(n) asm volatile("s_waitcnt lgkmcnt(" #n ")" ::: "memory")
; #define PG8_BAR __builtin_amdgcn_s_barrier()
; #define PG8_SCHED __builtin_amdgcn_sched_barrier(0)
; template <class Epi, class Sched, bool ALIGN_EPI = false, bool SP2 = false, bool SLIVER = false>
; __device__ __forceinline__ void gemm_phase(PG8_LAS unsigned char* lds, const Gemm g, const Sched& S, const Epi& E) {
;     ...
;             const bool last = (t == nt - 2);
;             const char* a1 = cA + (size_t)(t + 1) * kstep;
;             const char* a2 = last ? nA : cA + (size_t)(t + 2) * kstep; const char* b2 = last ? nB : cB + (size_t)(t + 2) * kstep;
;             const char* a3 = a2 + kstep; const char* b3 = b2 + kstep;
;             const char* s1 = cS + (size_t)(t + 1) * kstep; const char* s2 = last ? nS : cS + (size_t)(t + 2) * kstep;
;             if (last && has_next) S.a_ready(nxt);
;             if constexpr (SP2) {
;             PG8_LDB(B0, 0, 0); PG8_LDB(B1, 0, 1); PG8_SCHED; PG8_LDA(At, 0, 0); PG8_STAGE(PG8_SA(1, 1), a1 + hstep, voffA); PG8_STAGE_S(1, s1);
;             PG8_WAIT_V89(); PG8_WAIT_L(0); PG8_BAR; PG8_MMA(0, 0, At, B0); PG8_MMA(0, 1, At, B1); PG8_BAR; PG8_SCHED;
.LBB0_811:
	s_add_u32 s13, s90, s62
	s_addc_u32 s40, s91, s63
	s_add_u32 s13, s13, 0x100
	s_addc_u32 s66, s40, 0
	s_add_u32 s68, s2, s62
	s_addc_u32 s67, s3, s63
	s_add_i32 s69, 0, 0x10000
	s_cmpk_eq_i32 s62, 0x2b00
	s_cselect_b64 s[80:81], -1, 0
	s_and_b64 s[40:41], s[80:81], exec
	s_cselect_b32 s41, s85, s66
	s_cselect_b32 s40, s84, s13
	v_add_u32_e32 v66, s69, v220
	s_cselect_b32 s67, s87, s67
	s_cselect_b32 s66, s86, s68
	s_add_i32 s13, 0, 0x14000
	ds_read_b128 v[154:157], v66
	ds_read_b128 v[158:161], v66 offset:1024
	ds_read_b128 v[162:165], v66 offset:2048
	ds_read_b128 v[174:177], v66 offset:3072
	v_add_u32_e32 v66, s13, v220
	ds_read_b128 v[184:187], v66
	ds_read_b128 v[188:191], v66 offset:1024
	ds_read_b128 v[192:195], v66 offset:2048
	ds_read_b128 v[180:183], v66 offset:3072
	v_lshl_add_u64 v[146:147], v[214:215], 0, s[62:63]
	v_lshl_add_u64 v[148:149], v[146:147], 0, s[8:9]
	s_add_i32 m0, s19, 0xc000
	s_mov_b64 s[94:95], 0x210080
	ds_read_b128 v[66:69], v223
	ds_read_b128 v[70:73], v223 offset:1024
	ds_read_b128 v[74:77], v223 offset:2048
	ds_read_b128 v[78:81], v223 offset:3072
	ds_read_b128 v[216:219], v223 offset:4096
	ds_read_b128 v[224:227], v223 offset:5120
	ds_read_b128 v[228:231], v223 offset:6144
	ds_read_b128 v[232:235], v223 offset:7168
	global_load_lds_dwordx4 v[148:149], off
	v_lshl_add_u64 v[146:147], v[146:147], 0, s[94:95]
	s_add_i32 m0, s19, 0xe000
	s_nop 0
	global_load_lds_dwordx4 v[146:147], off
	v_lshl_add_u64 v[146:147], v[212:213], 0, s[62:63]
	s_add_i32 m0, s96, 0x20800
	s_nop 0
	global_load_lds_dword v[146:147], off
	s_waitcnt vmcnt(9)
	s_waitcnt lgkmcnt(0)
	s_setprio 1
	s_barrier
	v_mfma_f32_16x16x32_bf16 v[146:149], v[154:157], v[66:69], v[170:173]
	v_mfma_f32_16x16x32_bf16 v[146:149], v[158:161], v[70:73], v[146:149]
	v_mfma_f32_16x16x32_bf16 v[150:153], v[162:165], v[66:69], v[166:169]
	v_mfma_f32_16x16x32_bf16 v[150:153], v[174:177], v[70:73], v[150:153]
	v_mfma_f32_16x16x32_bf16 v[134:137], v[154:157], v[74:77], v[134:137]
	v_mfma_f32_16x16x32_bf16 v[134:137], v[158:161], v[78:81], v[134:137]
	v_mfma_f32_16x16x32_bf16 v[130:133], v[162:165], v[74:77], v[130:133]
	v_mfma_f32_16x16x32_bf16 v[130:133], v[174:177], v[78:81], v[130:133]
	v_mfma_f32_16x16x32_bf16 v[118:121], v[154:157], v[216:219], v[118:121]
	v_mfma_f32_16x16x32_bf16 v[118:121], v[158:161], v[224:227], v[118:121]
	v_mfma_f32_16x16x32_bf16 v[114:117], v[162:165], v[216:219], v[114:117]
	v_mfma_f32_16x16x32_bf16 v[114:117], v[174:177], v[224:227], v[114:117]
	v_mfma_f32_16x16x32_bf16 v[102:105], v[154:157], v[228:231], v[102:105]
	v_mfma_f32_16x16x32_bf16 v[102:105], v[158:161], v[232:235], v[102:105]
	v_mfma_f32_16x16x32_bf16 v[98:101], v[162:165], v[228:231], v[98:101]
	v_mfma_f32_16x16x32_bf16 v[98:101], v[174:177], v[232:235], v[98:101]
	s_setprio 0
	s_setprio 1
	v_mfma_f32_16x16x32_bf16 v[142:145], v[184:187], v[66:69], v[142:145]
	v_mfma_f32_16x16x32_bf16 v[142:145], v[188:191], v[70:73], v[142:145]
	v_mfma_f32_16x16x32_bf16 v[66:69], v[192:195], v[66:69], v[138:141]
	v_mfma_f32_16x16x32_bf16 v[138:141], v[180:183], v[70:73], v[66:69]
	v_mfma_f32_16x16x32_bf16 v[66:69], v[184:187], v[74:77], v[126:129]
	v_mfma_f32_16x16x32_bf16 v[126:129], v[188:191], v[78:81], v[66:69]
	v_mfma_f32_16x16x32_bf16 v[66:69], v[192:195], v[74:77], v[122:125]
	v_mfma_f32_16x16x32_bf16 v[122:125], v[180:183], v[78:81], v[66:69]
	v_mfma_f32_16x16x32_bf16 v[66:69], v[184:187], v[216:219], v[110:113]
	v_mfma_f32_16x16x32_bf16 v[110:113], v[188:191], v[224:227], v[66:69]
	v_mfma_f32_16x16x32_bf16 v[66:69], v[192:195], v[216:219], v[106:109]
	v_mfma_f32_16x16x32_bf16 v[106:109], v[180:183], v[224:227], v[66:69]
	v_mfma_f32_16x16x32_bf16 v[66:69], v[184:187], v[228:231], v[94:97]
	v_mfma_f32_16x16x32_bf16 v[94:97], v[188:191], v[232:235], v[66:69]
	v_mfma_f32_16x16x32_bf16 v[66:69], v[192:195], v[228:231], v[90:93]
	v_mfma_f32_16x16x32_bf16 v[90:93], v[180:183], v[232:235], v[66:69]
	s_barrier
; #define PG8_SB(B) __builtin_amdgcn_rcpf(1.f + expneg(B))
; #define PG8_SB(B) __builtin_amdgcn_rcpf(1.f + expneg(B))
; #define PG8_STAGE(bufoff, gbase, voff) do { _Pragma("unroll") for (int _i = 0; _i < 2; ++_i) \
;         __builtin_amdgcn_global_load_lds((const unsigned*)((const char*)(gbase) + (size_t)_i * qstep + (voff)[0]), (PG8_LAS unsigned*)(lds + (bufoff) + ldsw + _i * 8192), 16, 0, 0); } while (0)
; #define PG8_LDA(dst, b, h) do { _Pragma("unroll") for (int m = 0; m < 4; ++m) _Pragma("unroll") for (int k = 0; k < 2; ++k) dst[m][k] = *(const PG8_LAS bf16x8*)(lds + PG8_SA(b, h) + aoff + m * 2048 + k * 1024); } while (0)
; #define PG8_MMA(ai, bj, At, Bt) do { __builtin_amdgcn_s_setprio(1); _Pragma("unroll") for (int m = 0; m < 4; ++m) _Pragma("unroll") for (int n = 0; n < 2; ++n) _Pragma("unroll") for (int k = 0; k < 2; ++k) \
;         acc[ai][bj][m][n] = __builtin_amdgcn_mfma_f32_16x16x32_bf16(Bt[n][k], At[m][k], acc[ai][bj][m][n], 0, 0, 0); __builtin_amdgcn_s_setprio(0); } while (0)
; #define PG8_WAIT_V89() do { if constexpr (SLIVER) PG8_WAIT_V(9); else PG8_WAIT_V(8); } while (0)
; #define PG8_LDS_S(b) do { if constexpr (SLIVER) { Sf[0] = *(const PG8_LAS bf16x8*)(lds + STAGE_BYTES + (b) * 2048 + soff0); Sf[1] = *(const PG8_LAS bf16x8*)(lds + STAGE_BYTES + (b) * 2048 + (soff0 ^ 64)); } } while (0)
; #define PG8_WAIT_L(n) asm volatile("s_waitcnt lgkmcnt(" #n ")" ::: "memory")
; #define PG8_BAR __builtin_amdgcn_s_barrier()
; #define PG8_SCHED __builtin_amdgcn_sched_barrier(0)
; template <class Epi, class Sched, bool ALIGN_EPI = false, bool SP2 = false, bool SLIVER = false>
; __device__ __forceinline__ void gemm_phase(PG8_LAS unsigned char* lds, const Gemm g, const Sched& S, const Epi& E) {
;     ...
;             PG8_LDA(At, 0, 1); PG8_LDS_S(0); PG8_STAGE(PG8_SB(0, 0), b2, voffB); PG8_STAGE(PG8_SB(0, 1), b2 + hstep, voffB); PG8_STAGE(PG8_SA(0, 0), a2, voffA);
;             PG8_WAIT_V89(); PG8_WAIT_L(0); PG8_BAR; PG8_MMA(1, 0, At, B0); PG8_MMA(1, 1, At, B1); PG8_MMA_S(); PG8_BAR; PG8_SCHED;
	s_setprio 0
	s_add_i32 s68, 0, 0x20000
	v_lshl_add_u64 v[216:217], s[66:67], 0, v[198:199]
	s_add_i32 s66, s69, s18
	v_add_u32_e32 v74, s68, v221
	v_add_u32_e32 v75, s68, v222
	s_mov_b32 m0, s66
	ds_read_b128 v[66:69], v223 offset:16384
	ds_read_b128 v[70:73], v223 offset:17408
	ds_read_b128 v[224:227], v223 offset:18432
	ds_read_b128 v[228:231], v223 offset:19456
	ds_read_b128 v[232:235], v223 offset:20480
	ds_read_b128 v[240:243], v223 offset:21504
	ds_read_b128 v[244:247], v223 offset:22528
	ds_read_b128 v[248:251], v223 offset:23552
	ds_read_b128 v[166:169], v74
	ds_read_b128 v[170:173], v75
	global_load_lds_dwordx4 v[216:217], off
	v_lshl_add_u64 v[74:75], v[216:217], 0, s[64:65]
	s_add_i32 m0, s66, 0x2000
	s_add_i32 s13, s13, s18
	global_load_lds_dwordx4 v[74:75], off
	v_lshl_add_u64 v[74:75], v[216:217], 0, s[0:1]
	s_mov_b32 m0, s13
	v_lshl_add_u64 v[218:219], s[40:41], 0, v[196:197]
	global_load_lds_dwordx4 v[74:75], off
	v_lshl_add_u64 v[74:75], v[216:217], 0, s[74:75]
	s_add_i32 m0, s13, 0x2000
	s_nop 0
	global_load_lds_dwordx4 v[74:75], off
	s_mov_b32 m0, s19
	v_lshl_add_u64 v[74:75], v[218:219], 0, s[64:65]
	global_load_lds_dwordx4 v[218:219], off
	s_mov_b32 m0, s52
	s_nop 0
	global_load_lds_dwordx4 v[74:75], off
	s_waitcnt vmcnt(9)
	s_waitcnt lgkmcnt(0)
	s_setprio 1
	s_barrier
	v_mfma_f32_16x16x32_bf16 v[74:77], v[154:157], v[66:69], v[86:89]
	v_mfma_f32_16x16x32_bf16 v[74:77], v[158:161], v[70:73], v[74:77]
	v_mfma_f32_16x16x32_bf16 v[78:81], v[162:165], v[66:69], v[82:85]
	v_mfma_f32_16x16x32_bf16 v[78:81], v[174:177], v[70:73], v[78:81]
	v_mfma_f32_16x16x32_bf16 v[54:57], v[154:157], v[224:227], v[54:57]
	v_mfma_f32_16x16x32_bf16 v[54:57], v[158:161], v[228:231], v[54:57]
	v_mfma_f32_16x16x32_bf16 v[50:53], v[162:165], v[224:227], v[50:53]
	v_mfma_f32_16x16x32_bf16 v[50:53], v[174:177], v[228:231], v[50:53]
	v_mfma_f32_16x16x32_bf16 v[38:41], v[154:157], v[232:235], v[38:41]
	v_mfma_f32_16x16x32_bf16 v[38:41], v[158:161], v[240:243], v[38:41]
	v_mfma_f32_16x16x32_bf16 v[34:37], v[162:165], v[232:235], v[34:37]
	v_mfma_f32_16x16x32_bf16 v[34:37], v[174:177], v[240:243], v[34:37]
	v_mfma_f32_16x16x32_bf16 v[22:25], v[154:157], v[244:247], v[22:25]
	v_mfma_f32_16x16x32_bf16 v[22:25], v[158:161], v[248:251], v[22:25]
	v_mfma_f32_16x16x32_bf16 v[18:21], v[162:165], v[244:247], v[18:21]
	v_mfma_f32_16x16x32_bf16 v[18:21], v[174:177], v[248:251], v[18:21]
	s_setprio 0
	s_setprio 1
	v_mfma_f32_16x16x32_bf16 v[62:65], v[184:187], v[66:69], v[62:65]
	v_mfma_f32_16x16x32_bf16 v[62:65], v[188:191], v[70:73], v[62:65]
	v_mfma_f32_16x16x32_bf16 v[58:61], v[192:195], v[66:69], v[58:61]
	v_mfma_f32_16x16x32_bf16 v[58:61], v[180:183], v[70:73], v[58:61]
	v_mfma_f32_16x16x32_bf16 v[46:49], v[184:187], v[224:227], v[46:49]
	v_mfma_f32_16x16x32_bf16 v[46:49], v[188:191], v[228:231], v[46:49]
	v_mfma_f32_16x16x32_bf16 v[42:45], v[192:195], v[224:227], v[42:45]
	v_mfma_f32_16x16x32_bf16 v[42:45], v[180:183], v[228:231], v[42:45]
	v_mfma_f32_16x16x32_bf16 v[30:33], v[184:187], v[232:235], v[30:33]
	v_mfma_f32_16x16x32_bf16 v[30:33], v[188:191], v[240:243], v[30:33]
	v_mfma_f32_16x16x32_bf16 v[26:29], v[192:195], v[232:235], v[26:29]
	v_mfma_f32_16x16x32_bf16 v[26:29], v[180:183], v[240:243], v[26:29]
	v_mfma_f32_16x16x32_bf16 v[14:17], v[184:187], v[244:247], v[14:17]
	v_mfma_f32_16x16x32_bf16 v[14:17], v[188:191], v[248:251], v[14:17]
	v_mfma_f32_16x16x32_bf16 v[10:13], v[192:195], v[244:247], v[10:13]
	v_mfma_f32_16x16x32_bf16 v[10:13], v[180:183], v[248:251], v[10:13]
	s_setprio 0
	s_setprio 1
	s_and_b64 vcc, exec, s[82:83]
	s_cbranch_vccz .Lslv_b2
	v_mfma_f32_16x16x32_bf16 v[66:69], v[184:187], v[166:169], v[6:9]
	v_mfma_f32_16x16x32_bf16 v[66:69], v[188:191], v[170:173], v[66:69]
	v_mfma_f32_16x16x32_bf16 v[70:73], v[192:195], v[166:169], v[2:5]
	v_mfma_f32_16x16x32_bf16 v[70:73], v[180:183], v[170:173], v[70:73]
	s_branch .LBB0_815
.LBB0_813:
.Lslv_b2:
	v_mfma_f32_16x16x32_bf16 v[6:9], v[154:157], v[166:169], v[6:9]
	v_mfma_f32_16x16x32_bf16 v[66:69], v[158:161], v[170:173], v[6:9]
	v_mfma_f32_16x16x32_bf16 v[2:5], v[162:165], v[166:169], v[2:5]
	v_mfma_f32_16x16x32_bf16 v[70:73], v[174:177], v[170:173], v[2:5]

; #define PG8_STAGE(bufoff, gbase, voff) do { _Pragma("unroll") for (int _i = 0; _i < 2; ++_i) \
;         __builtin_amdgcn_global_load_lds((const unsigned*)((const char*)(gbase) + (size_t)_i * qstep + (voff)[0]), (PG8_LAS unsigned*)(lds + (bufoff) + ldsw + _i * 8192), 16, 0, 0); } while (0)
; #define PG8_LDA(dst, b, h) do { _Pragma("unroll") for (int m = 0; m < 4; ++m) _Pragma("unroll") for (int k = 0; k < 2; ++k) dst[m][k] = *(const PG8_LAS bf16x8*)(lds + PG8_SA(b, h) + aoff + m * 2048 + k * 1024); } while (0)
; #define PG8_LDB(dst, b, h) do { _Pragma("unroll") for (int n = 0; n < 2; ++n) _Pragma("unroll") for (int k = 0; k < 2; ++k) dst[n][k] = *(const PG8_LAS bf16x8*)(lds + PG8_SB(b, h) + boff + n * 2048 + k * 1024); } while (0)
; #define PG8_MMA(ai, bj, At, Bt) do { __builtin_amdgcn_s_setprio(1); _Pragma("unroll") for (int m = 0; m < 4; ++m) _Pragma("unroll") for (int n = 0; n < 2; ++n) _Pragma("unroll") for (int k = 0; k < 2; ++k) \
;         acc[ai][bj][m][n] = __builtin_amdgcn_mfma_f32_16x16x32_bf16(Bt[n][k], At[m][k], acc[ai][bj][m][n], 0, 0, 0); __builtin_amdgcn_s_setprio(0); } while (0)
; #define PG8_WAIT_V89() do { if constexpr (SLIVER) PG8_WAIT_V(9); else PG8_WAIT_V(8); } while (0)
; #define PG8_WAIT_L(n) asm volatile("s_waitcnt lgkmcnt(" #n ")" ::: "memory")
; #define PG8_BAR __builtin_amdgcn_s_barrier()
; #define PG8_SCHED __builtin_amdgcn_sched_barrier(0)
; template <class Epi, class Sched, bool ALIGN_EPI = false, bool SP2 = false, bool SLIVER = false>
; __device__ __forceinline__ void gemm_phase(PG8_LAS unsigned char* lds, const Gemm g, const Sched& S, const Epi& E) {
;     ...
;             const bool last = (t == nt - 2);
;             const char* a1 = cA + (size_t)(t + 1) * kstep;
;             const char* a2 = last ? nA : cA + (size_t)(t + 2) * kstep; const char* b2 = last ? nB : cB + (size_t)(t + 2) * kstep;
;             const char* a3 = a2 + kstep; const char* b3 = b2 + kstep;
;             const char* s1 = cS + (size_t)(t + 1) * kstep; const char* s2 = last ? nS : cS + (size_t)(t + 2) * kstep;
;             if (last && has_next) S.a_ready(nxt);
;             if constexpr (SP2) {
;             PG8_LDB(B0, 0, 0); PG8_LDB(B1, 0, 1); PG8_SCHED; PG8_LDA(At, 0, 0); PG8_STAGE(PG8_SA(1, 1), a1 + hstep, voffA); PG8_STAGE_S(1, s1);
;             PG8_WAIT_V89(); PG8_WAIT_L(0); PG8_BAR; PG8_MMA(0, 0, At, B0); PG8_MMA(0, 1, At, B1); PG8_BAR; PG8_SCHED;
.LBB0_934:
	s_cmp_eq_u32 s66, s62
	s_cselect_b64 s[80:81], -1, 0
	s_add_u32 s12, s42, s62
	s_addc_u32 s13, s43, s63
	s_add_u32 s40, s12, 0x100
	s_addc_u32 s41, s13, 0
	s_and_b64 s[12:13], s[80:81], exec
	s_cselect_b32 s41, s95, s41
	s_cselect_b32 s40, s94, s40
	s_add_u32 s68, s17, s62
	s_addc_u32 s69, s45, s63
	s_add_i32 s76, 0, 0x10000
	s_and_b64 s[12:13], s[80:81], exec
	v_add_u32_e32 v138, s76, v212
	s_cselect_b32 s13, s97, s69
	s_cselect_b32 s12, s96, s68
	s_add_i32 s68, 0, 0x14000
	ds_read_b128 v[146:149], v138
	ds_read_b128 v[150:153], v138 offset:1024
	ds_read_b128 v[154:157], v138 offset:2048
	ds_read_b128 v[158:161], v138 offset:3072
	v_add_u32_e32 v138, s68, v212
	ds_read_b128 v[166:169], v138
	ds_read_b128 v[170:173], v138 offset:1024
	ds_read_b128 v[174:177], v138 offset:2048
	ds_read_b128 v[162:165], v138 offset:3072
	v_lshl_add_u64 v[202:203], v[198:199], 0, s[62:63]
	s_mov_b64 vcc, 0x90080
	v_lshl_add_u64 v[208:209], v[202:203], 0, vcc
	s_add_i32 m0, s93, 0xc000
	s_mov_b64 vcc, 0xd8080
	ds_read_b128 v[138:141], v215
	ds_read_b128 v[142:145], v215 offset:1024
	ds_read_b128 v[180:183], v215 offset:2048
	ds_read_b128 v[184:187], v215 offset:3072
	ds_read_b128 v[216:219], v215 offset:4096
	ds_read_b128 v[220:223], v215 offset:5120
	ds_read_b128 v[224:227], v215 offset:6144
	ds_read_b128 v[228:231], v215 offset:7168
	global_load_lds_dwordx4 v[208:209], off
	v_lshl_add_u64 v[202:203], v[202:203], 0, vcc
	s_add_i32 m0, s93, 0xe000
	s_nop 0
	global_load_lds_dwordx4 v[202:203], off
	v_lshl_add_u64 v[202:203], v[200:201], 0, s[62:63]
	s_add_i32 m0, s50, 0x20800
	s_nop 0
	global_load_lds_dword v[202:203], off
	s_waitcnt vmcnt(9)
	s_waitcnt lgkmcnt(0)
	s_setprio 1
	s_barrier
	v_mfma_f32_16x16x32_bf16 v[134:137], v[146:149], v[138:141], v[134:137]
	v_mfma_f32_16x16x32_bf16 v[134:137], v[150:153], v[142:145], v[134:137]
	v_mfma_f32_16x16x32_bf16 v[130:133], v[154:157], v[138:141], v[130:133]
	v_mfma_f32_16x16x32_bf16 v[130:133], v[158:161], v[142:145], v[130:133]
	v_mfma_f32_16x16x32_bf16 v[126:129], v[146:149], v[180:183], v[126:129]
	v_mfma_f32_16x16x32_bf16 v[126:129], v[150:153], v[184:187], v[126:129]
	v_mfma_f32_16x16x32_bf16 v[122:125], v[154:157], v[180:183], v[122:125]
	v_mfma_f32_16x16x32_bf16 v[122:125], v[158:161], v[184:187], v[122:125]
	v_mfma_f32_16x16x32_bf16 v[114:117], v[146:149], v[216:219], v[114:117]
	v_mfma_f32_16x16x32_bf16 v[114:117], v[150:153], v[220:223], v[114:117]
	v_mfma_f32_16x16x32_bf16 v[106:109], v[154:157], v[216:219], v[106:109]
	v_mfma_f32_16x16x32_bf16 v[106:109], v[158:161], v[220:223], v[106:109]
	v_mfma_f32_16x16x32_bf16 v[98:101], v[146:149], v[224:227], v[98:101]
	v_mfma_f32_16x16x32_bf16 v[98:101], v[150:153], v[228:231], v[98:101]
	v_mfma_f32_16x16x32_bf16 v[90:93], v[154:157], v[224:227], v[90:93]
	v_mfma_f32_16x16x32_bf16 v[90:93], v[158:161], v[228:231], v[90:93]
	s_setprio 0
	s_setprio 1
	v_mfma_f32_16x16x32_bf16 v[118:121], v[166:169], v[138:141], v[118:121]
	v_mfma_f32_16x16x32_bf16 v[118:121], v[170:173], v[142:145], v[118:121]
	v_mfma_f32_16x16x32_bf16 v[110:113], v[174:177], v[138:141], v[110:113]
	v_mfma_f32_16x16x32_bf16 v[110:113], v[162:165], v[142:145], v[110:113]
	v_mfma_f32_16x16x32_bf16 v[102:105], v[166:169], v[180:183], v[102:105]
	v_mfma_f32_16x16x32_bf16 v[102:105], v[170:173], v[184:187], v[102:105]
	v_mfma_f32_16x16x32_bf16 v[94:97], v[174:177], v[180:183], v[94:97]
	v_mfma_f32_16x16x32_bf16 v[94:97], v[162:165], v[184:187], v[94:97]
	v_mfma_f32_16x16x32_bf16 v[86:89], v[166:169], v[216:219], v[86:89]
	v_mfma_f32_16x16x32_bf16 v[86:89], v[170:173], v[220:223], v[86:89]
	v_mfma_f32_16x16x32_bf16 v[82:85], v[174:177], v[216:219], v[82:85]
	v_mfma_f32_16x16x32_bf16 v[82:85], v[162:165], v[220:223], v[82:85]
	v_mfma_f32_16x16x32_bf16 v[78:81], v[166:169], v[224:227], v[78:81]
	v_mfma_f32_16x16x32_bf16 v[78:81], v[170:173], v[228:231], v[78:81]
	v_mfma_f32_16x16x32_bf16 v[74:77], v[174:177], v[224:227], v[74:77]
	v_mfma_f32_16x16x32_bf16 v[74:77], v[162:165], v[228:231], v[74:77]
	s_barrier
; #define PG8_SB(B) __builtin_amdgcn_rcpf(1.f + expneg(B))
; #define PG8_SB(B) __builtin_amdgcn_rcpf(1.f + expneg(B))
; #define PG8_STAGE(bufoff, gbase, voff) do { _Pragma("unroll") for (int _i = 0; _i < 2; ++_i) \
;         __builtin_amdgcn_global_load_lds((const unsigned*)((const char*)(gbase) + (size_t)_i * qstep + (voff)[0]), (PG8_LAS unsigned*)(lds + (bufoff) + ldsw + _i * 8192), 16, 0, 0); } while (0)
; #define PG8_LDA(dst, b, h) do { _Pragma("unroll") for (int m = 0; m < 4; ++m) _Pragma("unroll") for (int k = 0; k < 2; ++k) dst[m][k] = *(const PG8_LAS bf16x8*)(lds + PG8_SA(b, h) + aoff + m * 2048 + k * 1024); } while (0)
; #define PG8_MMA(ai, bj, At, Bt) do { __builtin_amdgcn_s_setprio(1); _Pragma("unroll") for (int m = 0; m < 4; ++m) _Pragma("unroll") for (int n = 0; n < 2; ++n) _Pragma("unroll") for (int k = 0; k < 2; ++k) \
;         acc[ai][bj][m][n] = __builtin_amdgcn_mfma_f32_16x16x32_bf16(Bt[n][k], At[m][k], acc[ai][bj][m][n], 0, 0, 0); __builtin_amdgcn_s_setprio(0); } while (0)
; #define PG8_WAIT_V89() do { if constexpr (SLIVER) PG8_WAIT_V(9); else PG8_WAIT_V(8); } while (0)
; #define PG8_LDS_S(b) do { if constexpr (SLIVER) { Sf[0] = *(const PG8_LAS bf16x8*)(lds + STAGE_BYTES + (b) * 2048 + soff0); Sf[1] = *(const PG8_LAS bf16x8*)(lds + STAGE_BYTES + (b) * 2048 + (soff0 ^ 64)); } } while (0)
; #define PG8_WAIT_L(n) asm volatile("s_waitcnt lgkmcnt(" #n ")" ::: "memory")
; #define PG8_BAR __builtin_amdgcn_s_barrier()
; #define PG8_SCHED __builtin_amdgcn_sched_barrier(0)
; template <class Epi, class Sched, bool ALIGN_EPI = false, bool SP2 = false, bool SLIVER = false>
; __device__ __forceinline__ void gemm_phase(PG8_LAS unsigned char* lds, const Gemm g, const Sched& S, const Epi& E) {
;     ...
;             PG8_LDA(At, 0, 1); PG8_LDS_S(0); PG8_STAGE(PG8_SB(0, 0), b2, voffB); PG8_STAGE(PG8_SB(0, 1), b2 + hstep, voffB); PG8_STAGE(PG8_SA(0, 0), a2, voffA);
;             PG8_WAIT_V89(); PG8_WAIT_L(0); PG8_BAR; PG8_MMA(1, 0, At, B0); PG8_MMA(1, 1, At, B1); PG8_MMA_S(); PG8_BAR; PG8_SCHED;
	s_setprio 0
	s_add_i32 s69, 0, 0x20000
	v_lshl_add_u64 v[202:203], s[12:13], 0, v[190:191]
	s_add_i32 s12, s76, s92
	v_add_u32_e32 v178, s69, v213
	v_add_u32_e32 v184, s69, v214
	s_mov_b32 m0, s12
	ds_read_b128 v[138:141], v215 offset:16384
	ds_read_b128 v[142:145], v215 offset:17408
	ds_read_b128 v[216:219], v215 offset:18432
	ds_read_b128 v[220:223], v215 offset:19456
	ds_read_b128 v[224:227], v215 offset:20480
	ds_read_b128 v[228:231], v215 offset:21504
	ds_read_b128 v[232:235], v215 offset:22528
	ds_read_b128 v[240:243], v215 offset:23552
	ds_read_b128 v[180:183], v178
	ds_read_b128 v[184:187], v184
	global_load_lds_dwordx4 v[202:203], off
	v_lshl_add_u64 v[208:209], v[202:203], 0, s[70:71]
	s_add_i32 m0, s12, 0x2000
	s_add_i32 s12, s68, s92
	global_load_lds_dwordx4 v[208:209], off
	v_lshl_add_u64 v[208:209], v[202:203], 0, s[46:47]
	s_mov_b32 m0, s12
	v_lshl_add_u64 v[210:211], s[40:41], 0, v[188:189]
	global_load_lds_dwordx4 v[208:209], off
	v_lshl_add_u64 v[208:209], v[202:203], 0, s[6:7]
	s_add_i32 m0, s12, 0x2000
	s_nop 0
	global_load_lds_dwordx4 v[208:209], off
	s_mov_b32 m0, s93
	v_lshl_add_u64 v[208:209], v[210:211], 0, s[70:71]
	global_load_lds_dwordx4 v[210:211], off
	s_mov_b32 m0, s48
	s_nop 0
	global_load_lds_dwordx4 v[208:209], off
	s_waitcnt vmcnt(9)
	s_waitcnt lgkmcnt(0)
	s_setprio 1
	s_barrier
	v_mfma_f32_16x16x32_bf16 v[70:73], v[146:149], v[138:141], v[70:73]
	v_mfma_f32_16x16x32_bf16 v[70:73], v[150:153], v[142:145], v[70:73]
	v_mfma_f32_16x16x32_bf16 v[66:69], v[154:157], v[138:141], v[66:69]
	v_mfma_f32_16x16x32_bf16 v[66:69], v[158:161], v[142:145], v[66:69]
	v_mfma_f32_16x16x32_bf16 v[62:65], v[146:149], v[216:219], v[62:65]
	v_mfma_f32_16x16x32_bf16 v[62:65], v[150:153], v[220:223], v[62:65]
	v_mfma_f32_16x16x32_bf16 v[58:61], v[154:157], v[216:219], v[58:61]
	v_mfma_f32_16x16x32_bf16 v[58:61], v[158:161], v[220:223], v[58:61]
	v_mfma_f32_16x16x32_bf16 v[50:53], v[146:149], v[224:227], v[50:53]
	v_mfma_f32_16x16x32_bf16 v[50:53], v[150:153], v[228:231], v[50:53]
	v_mfma_f32_16x16x32_bf16 v[42:45], v[154:157], v[224:227], v[42:45]
	v_mfma_f32_16x16x32_bf16 v[42:45], v[158:161], v[228:231], v[42:45]
	v_mfma_f32_16x16x32_bf16 v[34:37], v[146:149], v[232:235], v[34:37]
	v_mfma_f32_16x16x32_bf16 v[34:37], v[150:153], v[240:243], v[34:37]
	v_mfma_f32_16x16x32_bf16 v[26:29], v[154:157], v[232:235], v[26:29]
	v_mfma_f32_16x16x32_bf16 v[26:29], v[158:161], v[240:243], v[26:29]
	s_setprio 0
	s_setprio 1
	v_mfma_f32_16x16x32_bf16 v[54:57], v[166:169], v[138:141], v[54:57]
	v_mfma_f32_16x16x32_bf16 v[54:57], v[170:173], v[142:145], v[54:57]
	v_mfma_f32_16x16x32_bf16 v[46:49], v[174:177], v[138:141], v[46:49]
	v_mfma_f32_16x16x32_bf16 v[46:49], v[162:165], v[142:145], v[46:49]
	v_mfma_f32_16x16x32_bf16 v[38:41], v[166:169], v[216:219], v[38:41]
	v_mfma_f32_16x16x32_bf16 v[38:41], v[170:173], v[220:223], v[38:41]
	v_mfma_f32_16x16x32_bf16 v[30:33], v[174:177], v[216:219], v[30:33]
	v_mfma_f32_16x16x32_bf16 v[30:33], v[162:165], v[220:223], v[30:33]
	v_mfma_f32_16x16x32_bf16 v[22:25], v[166:169], v[224:227], v[22:25]
	v_mfma_f32_16x16x32_bf16 v[22:25], v[170:173], v[228:231], v[22:25]
	v_mfma_f32_16x16x32_bf16 v[18:21], v[174:177], v[224:227], v[18:21]
	v_mfma_f32_16x16x32_bf16 v[18:21], v[162:165], v[228:231], v[18:21]
	v_mfma_f32_16x16x32_bf16 v[14:17], v[166:169], v[232:235], v[14:17]
	v_mfma_f32_16x16x32_bf16 v[14:17], v[170:173], v[240:243], v[14:17]
	v_mfma_f32_16x16x32_bf16 v[10:13], v[174:177], v[232:235], v[10:13]
	v_mfma_f32_16x16x32_bf16 v[10:13], v[162:165], v[240:243], v[10:13]
	s_setprio 0
	s_setprio 1
	s_and_b64 vcc, exec, s[90:91]
	s_cbranch_vccz .Lslv_b3
	v_mfma_f32_16x16x32_bf16 v[138:141], v[166:169], v[180:183], v[6:9]
	v_mfma_f32_16x16x32_bf16 v[138:141], v[170:173], v[184:187], v[138:141]
	v_mfma_f32_16x16x32_bf16 v[142:145], v[174:177], v[180:183], v[2:5]
	v_mfma_f32_16x16x32_bf16 v[142:145], v[162:165], v[184:187], v[142:145]
	s_branch .LBB0_938
